# pool phases: rstd-table step of the in-loop pool phase also pipelined (6 row loads + interleaved wave reductions); conv epilogue vmcnt(0) waits relaxed to counted waits
# speedup vs baseline: 1.0025x; 1.0025x over previous
; __device__ __forceinline__ float wave_sum(float v) {
; #pragma unroll
;     for (int o = 1; o < 64; o <<= 1) v += __shfl_xor(v, o);
;     return v;
; }
; __device__ __forceinline__ float rstd_of(float ssq) { return __builtin_amdgcn_rsqf(ssq * (1.0f / DM) + RMS_EPS); }
; __device__ __forceinline__ void pool_phase(const float* __restrict__ x, const bf16_t* __restrict__ x16, const float* __restrict__ g, const float* rsq, bf16_t* __restrict__ pooled, LAS unsigned char* lds, int tid, int wid, int lane, int bid) {
;     ...
;         for (int i = wid; i < 47; i += NWAVE) { const int r = t0 - 15 + i; float val = 0.f;
;             if (r >= bstart && rsq) val = rstd_of(wave_sum(lane < 32 ? rsq[(size_t)r * 64 + lane] : 0.f));
;             else if (r >= bstart) { float s = 0.f; const f32x4* xr = (const f32x4*)(x + (size_t)r * DM);
; #pragma unroll
;                 for (int j = 0; j < 8; ++j) { const f32x4 v = xr[lane + 64 * j]; s += (v[0] * v[0] + v[1] * v[1]) + (v[2] * v[2] + v[3] * v[3]); }
;                 val = 1.0f / sqrtf(wave_sum(s) * (1.0f / DM) + RMS_EPS); }
;             if (lane == 0) rs[i] = val; }
.LBB0_618:
	s_ashr_i32 s10, s2, 31
	s_lshr_b32 s10, s10, 26
	s_add_i32 s10, s2, s10
	s_lshl_b32 s10, s10, 5
	s_andn2_b64 vcc, exec, s[14:15]
	s_and_b32 s25, s10, 0xfffff800
	s_cbranch_vccnz .LBB0_631
	s_mov_b32 s11, 0
	v_xor_b32_e32 v68, 1, v251
	v_lshlrev_b32_e32 v68, 2, v68
	v_xor_b32_e32 v69, 2, v251
	v_lshlrev_b32_e32 v69, 2, v69
	v_xor_b32_e32 v70, 4, v251
	v_lshlrev_b32_e32 v70, 2, v70
	v_xor_b32_e32 v71, 8, v251
	v_lshlrev_b32_e32 v71, 2, v71
	v_xor_b32_e32 v72, 16, v251
	v_lshlrev_b32_e32 v72, 2, v72
	v_xor_b32_e32 v73, 32, v251
	v_lshlrev_b32_e32 v73, 2, v73
	v_mov_b32_e32 v56, 0
	v_mov_b32_e32 v57, 0
	v_mov_b32_e32 v58, 0
	v_mov_b32_e32 v59, 0
	v_mov_b32_e32 v60, 0
	v_mov_b32_e32 v61, 0
	s_mov_b64 exec, s[4:5]
	s_add_i32 s26, s52, 0
	s_cmp_lt_i32 s26, s25
	s_cbranch_scc1 .LplB_s1_ld0
	s_lshl_b32 s10, s26, 8
	v_lshl_add_u64 v[74:75], v[14:15], 0, s[10:11]
	global_load_dword v56, v[74:75], off
.LplB_s1_ld0:
	s_add_i32 s26, s52, 8
	s_cmp_lt_i32 s26, s25
	s_cbranch_scc1 .LplB_s1_ld1
	s_lshl_b32 s10, s26, 8
	v_lshl_add_u64 v[74:75], v[14:15], 0, s[10:11]
	global_load_dword v57, v[74:75], off
.LplB_s1_ld1:
	s_add_i32 s26, s52, 16
	s_cmp_lt_i32 s26, s25
	s_cbranch_scc1 .LplB_s1_ld2
	s_lshl_b32 s10, s26, 8
	v_lshl_add_u64 v[74:75], v[14:15], 0, s[10:11]
	global_load_dword v58, v[74:75], off
.LplB_s1_ld2:
	s_add_i32 s26, s52, 24
	s_cmp_lt_i32 s26, s25
	s_cbranch_scc1 .LplB_s1_ld3
	s_lshl_b32 s10, s26, 8
	v_lshl_add_u64 v[74:75], v[14:15], 0, s[10:11]
	global_load_dword v59, v[74:75], off
.LplB_s1_ld3:
	s_add_i32 s26, s52, 32
	s_cmp_lt_i32 s26, s25
	s_cbranch_scc1 .LplB_s1_ld4
	s_lshl_b32 s10, s26, 8
	v_lshl_add_u64 v[74:75], v[14:15], 0, s[10:11]
	global_load_dword v60, v[74:75], off
.LplB_s1_ld4:
	s_add_i32 s26, s52, 40
	s_cmp_gt_i32 s23, 6
	s_cbranch_scc1 .LplB_s1_ld5
	s_cmp_lt_i32 s26, s25
	s_cbranch_scc1 .LplB_s1_ld5
	s_lshl_b32 s10, s26, 8
	v_lshl_add_u64 v[74:75], v[14:15], 0, s[10:11]
	global_load_dword v61, v[74:75], off
.LplB_s1_ld5:
	s_mov_b64 exec, -1
	s_waitcnt vmcnt(0)
	ds_bpermute_b32 v62, v68, v56
	ds_bpermute_b32 v63, v68, v57
	ds_bpermute_b32 v64, v68, v58
	ds_bpermute_b32 v65, v68, v59
	ds_bpermute_b32 v66, v68, v60
	ds_bpermute_b32 v67, v68, v61
	s_waitcnt lgkmcnt(0)
	v_add_f32_e32 v56, v56, v62
	v_add_f32_e32 v57, v57, v63
	v_add_f32_e32 v58, v58, v64
	v_add_f32_e32 v59, v59, v65
	v_add_f32_e32 v60, v60, v66
	v_add_f32_e32 v61, v61, v67
	ds_bpermute_b32 v62, v69, v56
	ds_bpermute_b32 v63, v69, v57
	ds_bpermute_b32 v64, v69, v58
	ds_bpermute_b32 v65, v69, v59
	ds_bpermute_b32 v66, v69, v60
	ds_bpermute_b32 v67, v69, v61
	s_waitcnt lgkmcnt(0)
	v_add_f32_e32 v56, v56, v62
	v_add_f32_e32 v57, v57, v63
	v_add_f32_e32 v58, v58, v64
	v_add_f32_e32 v59, v59, v65
	v_add_f32_e32 v60, v60, v66
	v_add_f32_e32 v61, v61, v67
	ds_bpermute_b32 v62, v70, v56
	ds_bpermute_b32 v63, v70, v57
	ds_bpermute_b32 v64, v70, v58
	ds_bpermute_b32 v65, v70, v59
	ds_bpermute_b32 v66, v70, v60
	ds_bpermute_b32 v67, v70, v61
	s_waitcnt lgkmcnt(0)
	v_add_f32_e32 v56, v56, v62
	v_add_f32_e32 v57, v57, v63
	v_add_f32_e32 v58, v58, v64
	v_add_f32_e32 v59, v59, v65
	v_add_f32_e32 v60, v60, v66
	v_add_f32_e32 v61, v61, v67
	ds_bpermute_b32 v62, v71, v56
	ds_bpermute_b32 v63, v71, v57
	ds_bpermute_b32 v64, v71, v58
	ds_bpermute_b32 v65, v71, v59
	ds_bpermute_b32 v66, v71, v60
	ds_bpermute_b32 v67, v71, v61
	s_waitcnt lgkmcnt(0)
	v_add_f32_e32 v56, v56, v62
	v_add_f32_e32 v57, v57, v63
	v_add_f32_e32 v58, v58, v64
	v_add_f32_e32 v59, v59, v65
	v_add_f32_e32 v60, v60, v66
	v_add_f32_e32 v61, v61, v67
	ds_bpermute_b32 v62, v72, v56
	ds_bpermute_b32 v63, v72, v57
	ds_bpermute_b32 v64, v72, v58
	ds_bpermute_b32 v65, v72, v59
	ds_bpermute_b32 v66, v72, v60
	ds_bpermute_b32 v67, v72, v61
	s_waitcnt lgkmcnt(0)
	v_add_f32_e32 v56, v56, v62
	v_add_f32_e32 v57, v57, v63
	v_add_f32_e32 v58, v58, v64
	v_add_f32_e32 v59, v59, v65
	v_add_f32_e32 v60, v60, v66
	v_add_f32_e32 v61, v61, v67
	ds_bpermute_b32 v62, v73, v56
	ds_bpermute_b32 v63, v73, v57
	ds_bpermute_b32 v64, v73, v58
	ds_bpermute_b32 v65, v73, v59
	ds_bpermute_b32 v66, v73, v60
	ds_bpermute_b32 v67, v73, v61
	s_waitcnt lgkmcnt(0)
	v_add_f32_e32 v56, v56, v62
	v_add_f32_e32 v57, v57, v63
	v_add_f32_e32 v58, v58, v64
	v_add_f32_e32 v59, v59, v65
	v_add_f32_e32 v60, v60, v66
	v_add_f32_e32 v61, v61, v67
	v_fmamk_f32 v56, v56, 0x3a000000, v243
	v_fmamk_f32 v57, v57, 0x3a000000, v243
	v_fmamk_f32 v58, v58, 0x3a000000, v243
	v_fmamk_f32 v59, v59, 0x3a000000, v243
	v_fmamk_f32 v60, v60, 0x3a000000, v243
	v_fmamk_f32 v61, v61, 0x3a000000, v243
	v_rsq_f32_e32 v56, v56
	v_rsq_f32_e32 v57, v57
	v_rsq_f32_e32 v58, v58
	v_rsq_f32_e32 v59, v59
	v_rsq_f32_e32 v60, v60
	v_rsq_f32_e32 v61, v61
	s_nop 0
	s_add_i32 s26, s52, 0
	s_cmp_lt_i32 s26, s25
	s_cbranch_scc0 .LplB_s1_z0
	v_mov_b32_e32 v56, 0
.LplB_s1_z0:
	s_add_i32 s26, s52, 8
	s_cmp_lt_i32 s26, s25
	s_cbranch_scc0 .LplB_s1_z1
	v_mov_b32_e32 v57, 0
.LplB_s1_z1:
	s_add_i32 s26, s52, 16
	s_cmp_lt_i32 s26, s25
	s_cbranch_scc0 .LplB_s1_z2
	v_mov_b32_e32 v58, 0
.LplB_s1_z2:
	s_add_i32 s26, s52, 24
	s_cmp_lt_i32 s26, s25
	s_cbranch_scc0 .LplB_s1_z3
	v_mov_b32_e32 v59, 0
.LplB_s1_z3:
	s_add_i32 s26, s52, 32
	s_cmp_lt_i32 s26, s25
	s_cbranch_scc0 .LplB_s1_z4
	v_mov_b32_e32 v60, 0
.LplB_s1_z4:
	s_add_i32 s26, s52, 40
	s_cmp_lt_i32 s26, s25
	s_cbranch_scc0 .LplB_s1_z5
	v_mov_b32_e32 v61, 0
.LplB_s1_z5:
	s_mov_b64 exec, s[6:7]
	v_mov_b32_e32 v74, s3
	ds_write_b32 v74, v56 offset:0
	ds_write_b32 v74, v57 offset:32
	ds_write_b32 v74, v58 offset:64
	ds_write_b32 v74, v59 offset:96
	ds_write_b32 v74, v60 offset:128
	s_cmp_gt_i32 s23, 6
	s_cbranch_scc1 .LplB_s1_done
	ds_write_b32 v74, v61 offset:160
.LplB_s1_done:
	s_mov_b64 exec, -1

; __device__ __forceinline__ unsigned pk2(float lo, float hi) { f32x2 v = {lo, hi}; bf16x2_t b = __builtin_convertvector(v, bf16x2_t); return __builtin_bit_cast(unsigned, b); }
; __device__ __forceinline__ float fast_sigmoid(float g) { return __builtin_amdgcn_rcpf(1.0f + __expf(-g)); }
;     __device__ __forceinline__ void operator()(const f32x4 (&acc)[2][2][4][2], const Unit& u, int wr, int wc, int fr, int fq) const {
;     ...
;         bf16_t* arow = act + (size_t)(u.pm * BM + g8) * DFF + f0;
; #pragma unroll
;         for (int n = 0; n < 2; ++n) {
;             const int f = f0 + 4 * n;
;             f32x4 wv0, wv1, wv2, bvv, wg0, wg1, wg2, bgg;
;             if (n == 0) { wv0 = pw[0]; wv1 = pw[1]; wv2 = pw[2]; bvv = pw[3]; wg0 = pw[4]; wg1 = pw[5]; wg2 = pw[6]; bgg = pw[7]; }
;             else { wv0 = pw2[0]; wv1 = pw2[1]; wv2 = pw2[2]; bvv = pw2[3]; wg0 = pw2[4]; wg1 = pw2[5]; wg2 = pw2[6]; bgg = pw2[7]; }
;             const f32x4 v6 = acc[1][0][2][n] * rs[6], v7 = acc[1][0][3][n] * rs[7], g6 = acc[1][1][2][n] * rs[6], g7 = acc[1][1][3][n] * rs[7];
;             f32x4 av2, av1, ag2, ag1;
; #pragma unroll
;             for (int e = 0; e < 4; ++e) { av2[e] = __shfl_up(v6[e], 1, 16); av1[e] = __shfl_up(v7[e], 1, 16); ag2[e] = __shfl_up(g6[e], 1, 16); ag1[e] = __shfl_up(g7[e], 1, 16); }
;             if (fr == 15) { *(f32x4*)(hrow + 2 * DFF2 + 4 * n) = v6; *(f32x4*)(hrow + 2 * DFF2 + HALF + 4 * n) = g6; *(f32x4*)(hrow + 3 * DFF2 + 4 * n) = v7; *(f32x4*)(hrow + 3 * DFF2 + HALF + 4 * n) = g7; }
; #pragma unroll
;             for (int j = 0; j < 8; ++j) {
;                 const f32x4 cv_ = acc[j >> 2][0][j & 3][n] * rs[j], cg_ = acc[j >> 2][1][j & 3][n] * rs[j];
;                 if (j < 2 && fr == 0) { *(f32x4*)(hrow + j * DFF2 + 4 * n) = cv_; *(f32x4*)(hrow + j * DFF2 + HALF + 4 * n) = cg_; }
;                 const f32x4 cv = bvv + wv0 * av2 + wv1 * av1 + wv2 * cv_, cg = bgg + wg0 * ag2 + wg1 * ag1 + wg2 * cg_;
;                 f32x4 o;
; #pragma unroll
;                 for (int e = 0; e < 4; ++e) o[e] = cg[e] * fast_sigmoid(cg[e]) * cv[e];
;                 u32x2 w; w.x = pk2(o[0], o[1]); w.y = pk2(o[2], o[3]);
;                 if (!(j < 2 && fr == 0)) *(u32x2*)(arow + (size_t)j * DFF + 4 * n) = w;
.LBB0_1098:
	s_or_b64 exec, exec, s[14:15]
	v_lshl_add_u32 v204, s60, 8, v254
	v_mov_b64_e32 v[202:203], s[74:75]
	s_movk_i32 s3, 0x2c00
	v_mad_i64_i32 v[202:203], s[14:15], v204, s3, v[202:203]
	v_lshl_add_u64 v[222:223], v[222:223], 1, v[202:203]
	v_pk_mul_f32 v[190:191], v[190:191], v[126:127] op_sel_hi:[1,0]
	v_pk_mul_f32 v[192:193], v[192:193], v[126:127] op_sel_hi:[1,0]
	v_pk_mul_f32 v[178:179], v[178:179], v[126:127] op_sel_hi:[1,0]
	v_pk_mul_f32 v[180:181], v[180:181], v[126:127] op_sel_hi:[1,0]
	s_and_saveexec_b64 s[14:15], s[10:11]
	s_xor_b64 s[14:15], exec, s[14:15]
	s_cbranch_execz .LBB0_1100
	s_waitcnt vmcnt(4) lgkmcnt(0)
	v_pk_fma_f32 v[202:203], v[146:147], v[240:241], v[166:167]
	v_pk_fma_f32 v[236:237], v[148:149], v[236:237], v[168:169]
	v_pk_fma_f32 v[202:203], v[154:155], v[232:233], v[202:203]
	v_pk_fma_f32 v[236:237], v[156:157], v[228:229], v[236:237]
	v_pk_fma_f32 v[202:203], v[158:159], v[178:179], v[202:203]
	v_pk_fma_f32 v[236:237], v[160:161], v[180:181], v[236:237]
	v_mul_f32_e32 v204, 0xbfb8aa3b, v202
	v_exp_f32_e32 v204, v204
	v_mul_f32_e32 v205, 0xbfb8aa3b, v203
	v_exp_f32_e32 v205, v205
	v_pk_fma_f32 v[238:239], v[130:131], v[238:239], v[142:143]
	v_add_f32_e32 v204, 1.0, v204
	v_rcp_f32_e32 v240, v204
	v_add_f32_e32 v205, 1.0, v205
	v_mul_f32_e32 v204, 0xbfb8aa3b, v236
	v_rcp_f32_e32 v241, v205
	v_exp_f32_e32 v204, v204
	v_mul_f32_e32 v205, 0xbfb8aa3b, v237
	v_exp_f32_e32 v205, v205
	v_pk_fma_f32 v[238:239], v[134:135], v[230:231], v[238:239]
	v_pk_mul_f32 v[202:203], v[202:203], v[240:241]
	v_pk_fma_f32 v[238:239], v[138:139], v[190:191], v[238:239]
	v_add_f32_e32 v204, 1.0, v204
	v_pk_mul_f32 v[202:203], v[238:239], v[202:203]
	v_rcp_f32_e32 v238, v204
	v_add_f32_e32 v204, 1.0, v205
	v_rcp_f32_e32 v239, v204
	v_pk_fma_f32 v[234:235], v[132:133], v[234:235], v[144:145]
	v_pk_mul_f32 v[236:237], v[236:237], v[238:239]
	v_pk_fma_f32 v[234:235], v[136:137], v[226:227], v[234:235]
	s_nop 0
	v_pk_fma_f32 v[234:235], v[140:141], v[192:193], v[234:235]
	s_nop 0
	v_pk_mul_f32 v[234:235], v[234:235], v[236:237]
	s_nop 0
	v_cvt_pk_bf16_f32 v235, v234, v235
	v_cvt_pk_bf16_f32 v234, v202, v203
	global_store_dwordx2 v[222:223], v[234:235], off

; __device__ __forceinline__ unsigned pk2(float lo, float hi) { f32x2 v = {lo, hi}; bf16x2_t b = __builtin_convertvector(v, bf16x2_t); return __builtin_bit_cast(unsigned, b); }
; __device__ __forceinline__ float fast_sigmoid(float g) { return __builtin_amdgcn_rcpf(1.0f + __expf(-g)); }
;     __device__ __forceinline__ void operator()(const f32x4 (&acc)[2][2][4][2], const Unit& u, int wr, int wc, int fr, int fq) const {
;     ...
;             for (int j = 0; j < 8; ++j) {
;                 const f32x4 cv_ = acc[j >> 2][0][j & 3][n] * rs[j], cg_ = acc[j >> 2][1][j & 3][n] * rs[j];
;                 if (j < 2 && fr == 0) { *(f32x4*)(hrow + j * DFF2 + 4 * n) = cv_; *(f32x4*)(hrow + j * DFF2 + HALF + 4 * n) = cg_; }
;                 const f32x4 cv = bvv + wv0 * av2 + wv1 * av1 + wv2 * cv_, cg = bgg + wg0 * ag2 + wg1 * ag1 + wg2 * cg_;
;                 f32x4 o;
; #pragma unroll
;                 for (int e = 0; e < 4; ++e) o[e] = cg[e] * fast_sigmoid(cg[e]) * cv[e];
;                 u32x2 w; w.x = pk2(o[0], o[1]); w.y = pk2(o[2], o[3]);
;                 if (!(j < 2 && fr == 0)) *(u32x2*)(arow + (size_t)j * DFF + 4 * n) = w;
;                 av2 = av1; av1 = cv_; ag2 = ag1; ag1 = cg_;
.LBB0_1102:
	s_or_b64 exec, exec, s[14:15]
	v_pk_mul_f32 v[174:175], v[174:175], v[126:127] op_sel:[0,1]
	v_pk_mul_f32 v[176:177], v[176:177], v[126:127] op_sel:[0,1]
	v_pk_mul_f32 v[170:171], v[170:171], v[126:127] op_sel:[0,1]
	v_pk_mul_f32 v[172:173], v[172:173], v[126:127] op_sel:[0,1]
	s_and_saveexec_b64 s[14:15], s[10:11]
	s_xor_b64 s[14:15], exec, s[14:15]
	s_cbranch_execz .LBB0_1104
	s_waitcnt vmcnt(7) lgkmcnt(0)
	v_pk_fma_f32 v[202:203], v[146:147], v[232:233], v[166:167]
	v_pk_fma_f32 v[228:229], v[148:149], v[228:229], v[168:169]
	v_pk_fma_f32 v[202:203], v[154:155], v[178:179], v[202:203]
	v_pk_fma_f32 v[228:229], v[156:157], v[180:181], v[228:229]
	v_pk_fma_f32 v[202:203], v[158:159], v[170:171], v[202:203]
	v_pk_fma_f32 v[228:229], v[160:161], v[172:173], v[228:229]
	v_mul_f32_e32 v204, 0xbfb8aa3b, v202
	v_exp_f32_e32 v204, v204
	v_mul_f32_e32 v205, 0xbfb8aa3b, v203
	v_exp_f32_e32 v205, v205
	v_pk_fma_f32 v[230:231], v[130:131], v[230:231], v[142:143]
	v_add_f32_e32 v204, 1.0, v204
	v_rcp_f32_e32 v232, v204
	v_add_f32_e32 v205, 1.0, v205
	v_mul_f32_e32 v204, 0xbfb8aa3b, v228
	v_rcp_f32_e32 v233, v205
	v_exp_f32_e32 v204, v204
	v_mul_f32_e32 v205, 0xbfb8aa3b, v229
	v_exp_f32_e32 v205, v205
	v_pk_fma_f32 v[230:231], v[134:135], v[190:191], v[230:231]
	v_pk_mul_f32 v[202:203], v[202:203], v[232:233]
	v_pk_fma_f32 v[230:231], v[138:139], v[174:175], v[230:231]
	v_add_f32_e32 v204, 1.0, v204
	v_pk_mul_f32 v[202:203], v[230:231], v[202:203]
	v_rcp_f32_e32 v230, v204
	v_add_f32_e32 v204, 1.0, v205
	v_rcp_f32_e32 v231, v204
	v_pk_fma_f32 v[226:227], v[132:133], v[226:227], v[144:145]
	v_pk_mul_f32 v[228:229], v[228:229], v[230:231]
	v_pk_fma_f32 v[226:227], v[136:137], v[192:193], v[226:227]
	s_nop 0
	v_pk_fma_f32 v[226:227], v[140:141], v[176:177], v[226:227]
	s_nop 0
	v_pk_mul_f32 v[226:227], v[226:227], v[228:229]
	s_nop 0
	v_cvt_pk_bf16_f32 v227, v226, v227
	v_cvt_pk_bf16_f32 v226, v202, v203
	v_add_co_u32_e32 v202, vcc, 0x2000, v222
	s_nop 1
	v_addc_co_u32_e32 v203, vcc, 0, v223, vcc
	global_store_dwordx2 v[202:203], v[226:227], off offset:3072

; __device__ __forceinline__ unsigned pk2(float lo, float hi) { f32x2 v = {lo, hi}; bf16x2_t b = __builtin_convertvector(v, bf16x2_t); return __builtin_bit_cast(unsigned, b); }
; __device__ __forceinline__ float fast_sigmoid(float g) { return __builtin_amdgcn_rcpf(1.0f + __expf(-g)); }
;     __device__ __forceinline__ void operator()(const f32x4 (&acc)[2][2][4][2], const Unit& u, int wr, int wc, int fr, int fq) const {
;     ...
;             for (int j = 0; j < 8; ++j) {
;                 const f32x4 cv_ = acc[j >> 2][0][j & 3][n] * rs[j], cg_ = acc[j >> 2][1][j & 3][n] * rs[j];
;                 if (j < 2 && fr == 0) { *(f32x4*)(hrow + j * DFF2 + 4 * n) = cv_; *(f32x4*)(hrow + j * DFF2 + HALF + 4 * n) = cg_; }
;                 const f32x4 cv = bvv + wv0 * av2 + wv1 * av1 + wv2 * cv_, cg = bgg + wg0 * ag2 + wg1 * ag1 + wg2 * cg_;
;                 f32x4 o;
; #pragma unroll
;                 for (int e = 0; e < 4; ++e) o[e] = cg[e] * fast_sigmoid(cg[e]) * cv[e];
;                 u32x2 w; w.x = pk2(o[0], o[1]); w.y = pk2(o[2], o[3]);
;                 if (!(j < 2 && fr == 0)) *(u32x2*)(arow + (size_t)j * DFF + 4 * n) = w;
;                 av2 = av1; av1 = cv_; ag2 = ag1; ag1 = cg_;
.LBB0_1106:
	s_or_b64 exec, exec, s[14:15]
	s_waitcnt lgkmcnt(0)
	v_pk_mul_f32 v[230:231], v[152:153], v[128:129] op_sel_hi:[1,0]
	v_pk_mul_f32 v[152:153], v[164:165], v[128:129] op_sel_hi:[1,0]
	v_pk_mul_f32 v[164:165], v[162:163], v[128:129] op_sel_hi:[1,0]
	s_waitcnt vmcnt(10)
	v_pk_fma_f32 v[162:163], v[146:147], v[178:179], v[166:167]
	v_pk_mul_f32 v[232:233], v[150:151], v[128:129] op_sel_hi:[1,0]
	v_pk_fma_f32 v[162:163], v[154:155], v[170:171], v[162:163]
	v_pk_fma_f32 v[150:151], v[148:149], v[180:181], v[168:169]
	v_pk_fma_f32 v[162:163], v[158:159], v[232:233], v[162:163]
	v_pk_fma_f32 v[150:151], v[156:157], v[172:173], v[150:151]
	v_mul_f32_e32 v178, 0xbfb8aa3b, v162
	v_mul_f32_e32 v179, 0xbfb8aa3b, v163
	v_exp_f32_e32 v178, v178
	v_exp_f32_e32 v179, v179
	v_pk_fma_f32 v[150:151], v[160:161], v[230:231], v[150:151]
	v_pk_fma_f32 v[180:181], v[132:133], v[192:193], v[144:145]
	v_add_f32_e32 v178, 1.0, v178
	v_add_f32_e32 v179, 1.0, v179
	v_rcp_f32_e32 v178, v178
	v_rcp_f32_e32 v179, v179
	v_pk_fma_f32 v[190:191], v[130:131], v[190:191], v[142:143]
	v_pk_fma_f32 v[180:181], v[136:137], v[176:177], v[180:181]
	v_pk_fma_f32 v[190:191], v[134:135], v[174:175], v[190:191]
	v_pk_mul_f32 v[162:163], v[162:163], v[178:179]
	v_mul_f32_e32 v178, 0xbfb8aa3b, v150
	v_mul_f32_e32 v179, 0xbfb8aa3b, v151
	v_exp_f32_e32 v178, v178
	v_exp_f32_e32 v179, v179
	v_pk_fma_f32 v[180:181], v[140:141], v[152:153], v[180:181]
	v_pk_fma_f32 v[190:191], v[138:139], v[164:165], v[190:191]
	v_add_f32_e32 v178, 1.0, v178
	v_add_f32_e32 v179, 1.0, v179
	v_rcp_f32_e32 v178, v178
	v_rcp_f32_e32 v179, v179
	s_movk_i32 s3, 0x5000
	v_pk_mul_f32 v[162:163], v[190:191], v[162:163]
	v_pk_mul_f32 v[102:103], v[102:103], v[106:107] op_sel:[0,1]
	v_pk_mul_f32 v[150:151], v[150:151], v[178:179]
	v_cvt_pk_bf16_f32 v178, v162, v163
	v_pk_mul_f32 v[150:151], v[180:181], v[150:151]
	v_mov_b32_e32 v180, v129
	v_cvt_pk_bf16_f32 v179, v150, v151
	v_add_co_u32_e32 v150, vcc, s3, v222
	v_pk_mul_f32 v[162:163], v[120:121], v[180:181] op_sel_hi:[1,0]
	s_nop 0
	v_addc_co_u32_e32 v151, vcc, 0, v223, vcc
	global_store_dwordx2 v[150:151], v[178:179], off offset:2048
	v_pk_mul_f32 v[178:179], v[118:119], v[180:181] op_sel_hi:[1,0]
	v_pk_fma_f32 v[118:119], v[146:147], v[170:171], v[166:167]
	v_pk_mul_f32 v[120:121], v[124:125], v[180:181] op_sel_hi:[1,0]
	v_pk_fma_f32 v[118:119], v[154:155], v[232:233], v[118:119]
	v_pk_mul_f32 v[124:125], v[122:123], v[180:181] op_sel_hi:[1,0]
	v_pk_fma_f32 v[118:119], v[158:159], v[178:179], v[118:119]
	v_pk_fma_f32 v[170:171], v[130:131], v[174:175], v[142:143]
	v_mul_f32_e32 v122, 0xbfb8aa3b, v118
	v_mul_f32_e32 v123, 0xbfb8aa3b, v119
	v_exp_f32_e32 v122, v122
	v_exp_f32_e32 v123, v123
	v_pk_fma_f32 v[170:171], v[134:135], v[164:165], v[170:171]
	s_mov_b32 s3, 0x8000
	v_add_f32_e32 v122, 1.0, v122
	v_add_f32_e32 v123, 1.0, v123
	v_rcp_f32_e32 v122, v122
	v_rcp_f32_e32 v123, v123
	v_pk_fma_f32 v[170:171], v[138:139], v[124:125], v[170:171]
	v_pk_fma_f32 v[164:165], v[130:131], v[164:165], v[142:143]
	v_pk_mul_f32 v[104:105], v[104:105], v[106:107] op_sel:[0,1]
	v_pk_mul_f32 v[118:119], v[118:119], v[122:123]
	v_pk_fma_f32 v[122:123], v[148:149], v[172:173], v[168:169]
	v_pk_mul_f32 v[118:119], v[170:171], v[118:119]
	v_pk_fma_f32 v[122:123], v[156:157], v[230:231], v[122:123]
	v_pk_fma_f32 v[172:173], v[132:133], v[176:177], v[144:145]
	v_pk_fma_f32 v[122:123], v[160:161], v[162:163], v[122:123]
	v_pk_fma_f32 v[172:173], v[136:137], v[152:153], v[172:173]
	v_mul_f32_e32 v170, 0xbfb8aa3b, v122
	v_mul_f32_e32 v171, 0xbfb8aa3b, v123
	v_exp_f32_e32 v170, v170
	v_exp_f32_e32 v171, v171
	v_pk_fma_f32 v[172:173], v[140:141], v[120:121], v[172:173]
	v_pk_fma_f32 v[164:165], v[134:135], v[124:125], v[164:165]
	v_add_f32_e32 v170, 1.0, v170
	v_add_f32_e32 v171, 1.0, v171
	v_rcp_f32_e32 v170, v170
	v_rcp_f32_e32 v171, v171
	v_pk_fma_f32 v[152:153], v[132:133], v[152:153], v[144:145]
	v_pk_fma_f32 v[124:125], v[130:131], v[124:125], v[142:143]
	v_pk_fma_f32 v[152:153], v[136:137], v[120:121], v[152:153]
	v_pk_mul_f32 v[122:123], v[122:123], v[170:171]
	v_pk_mul_f32 v[170:171], v[110:111], v[106:107] op_sel_hi:[1,0]
	v_pk_mul_f32 v[122:123], v[172:173], v[122:123]
	v_pk_fma_f32 v[110:111], v[146:147], v[232:233], v[166:167]
	v_cvt_pk_bf16_f32 v123, v122, v123
	v_cvt_pk_bf16_f32 v122, v118, v119
	v_add_co_u32_e32 v118, vcc, s3, v222
	v_pk_fma_f32 v[110:111], v[154:155], v[178:179], v[110:111]
	s_nop 0
	v_addc_co_u32_e32 v119, vcc, 0, v223, vcc
	v_pk_fma_f32 v[110:111], v[158:159], v[170:171], v[110:111]
	global_store_dwordx2 v[118:119], v[122:123], off offset:1024
	v_pk_mul_f32 v[122:123], v[112:113], v[106:107] op_sel_hi:[1,0]
	v_pk_mul_f32 v[112:113], v[116:117], v[106:107] op_sel_hi:[1,0]
	v_pk_mul_f32 v[116:117], v[114:115], v[106:107] op_sel_hi:[1,0]
	v_mul_f32_e32 v114, 0xbfb8aa3b, v110
	v_mul_f32_e32 v115, 0xbfb8aa3b, v111
	v_exp_f32_e32 v114, v114
	v_exp_f32_e32 v115, v115
	v_pk_fma_f32 v[164:165], v[138:139], v[116:117], v[164:165]
	v_pk_fma_f32 v[152:153], v[140:141], v[112:113], v[152:153]
	v_add_f32_e32 v114, 1.0, v114
	v_add_f32_e32 v115, 1.0, v115
	v_rcp_f32_e32 v114, v114
	v_rcp_f32_e32 v115, v115
	v_pk_fma_f32 v[124:125], v[134:135], v[116:117], v[124:125]
	v_pk_fma_f32 v[120:121], v[132:133], v[120:121], v[144:145]
	v_pk_fma_f32 v[124:125], v[138:139], v[102:103], v[124:125]
	v_pk_mul_f32 v[110:111], v[110:111], v[114:115]
	v_pk_fma_f32 v[114:115], v[148:149], v[230:231], v[168:169]
	v_pk_mul_f32 v[110:111], v[164:165], v[110:111]
	v_pk_fma_f32 v[114:115], v[156:157], v[162:163], v[114:115]
	v_pk_fma_f32 v[120:121], v[136:137], v[112:113], v[120:121]
; __device__ __forceinline__ unsigned pk2(float lo, float hi) { f32x2 v = {lo, hi}; bf16x2_t b = __builtin_convertvector(v, bf16x2_t); return __builtin_bit_cast(unsigned, b); }
; __device__ __forceinline__ float fast_sigmoid(float g) { return __builtin_amdgcn_rcpf(1.0f + __expf(-g)); }
;     __device__ __forceinline__ void operator()(const f32x4 (&acc)[2][2][4][2], const Unit& u, int wr, int wc, int fr, int fq) const {
;     ...
;         for (int n = 0; n < 2; ++n) {
;             const int f = f0 + 4 * n;
;             f32x4 wv0, wv1, wv2, bvv, wg0, wg1, wg2, bgg;
;             if (n == 0) { wv0 = pw[0]; wv1 = pw[1]; wv2 = pw[2]; bvv = pw[3]; wg0 = pw[4]; wg1 = pw[5]; wg2 = pw[6]; bgg = pw[7]; }
;             else { wv0 = pw2[0]; wv1 = pw2[1]; wv2 = pw2[2]; bvv = pw2[3]; wg0 = pw2[4]; wg1 = pw2[5]; wg2 = pw2[6]; bgg = pw2[7]; }
;             const f32x4 v6 = acc[1][0][2][n] * rs[6], v7 = acc[1][0][3][n] * rs[7], g6 = acc[1][1][2][n] * rs[6], g7 = acc[1][1][3][n] * rs[7];
;             f32x4 av2, av1, ag2, ag1;
; #pragma unroll
;             for (int e = 0; e < 4; ++e) { av2[e] = __shfl_up(v6[e], 1, 16); av1[e] = __shfl_up(v7[e], 1, 16); ag2[e] = __shfl_up(g6[e], 1, 16); ag1[e] = __shfl_up(g7[e], 1, 16); }
;             if (fr == 15) { *(f32x4*)(hrow + 2 * DFF2 + 4 * n) = v6; *(f32x4*)(hrow + 2 * DFF2 + HALF + 4 * n) = g6; *(f32x4*)(hrow + 3 * DFF2 + 4 * n) = v7; *(f32x4*)(hrow + 3 * DFF2 + HALF + 4 * n) = g7; }
; #pragma unroll
;             for (int j = 0; j < 8; ++j) {
;                 const f32x4 cv_ = acc[j >> 2][0][j & 3][n] * rs[j], cg_ = acc[j >> 2][1][j & 3][n] * rs[j];
;                 if (j < 2 && fr == 0) { *(f32x4*)(hrow + j * DFF2 + 4 * n) = cv_; *(f32x4*)(hrow + j * DFF2 + HALF + 4 * n) = cg_; }
;                 const f32x4 cv = bvv + wv0 * av2 + wv1 * av1 + wv2 * cv_, cg = bgg + wg0 * ag2 + wg1 * ag1 + wg2 * cg_;
;                 f32x4 o;
; #pragma unroll
;                 for (int e = 0; e < 4; ++e) o[e] = cg[e] * fast_sigmoid(cg[e]) * cv[e];
;                 u32x2 w; w.x = pk2(o[0], o[1]); w.y = pk2(o[2], o[3]);
;                 if (!(j < 2 && fr == 0)) *(u32x2*)(arow + (size_t)j * DFF + 4 * n) = w;
;                 av2 = av1; av1 = cv_; ag2 = ag1; ag1 = cg_;
;             }
	v_pk_fma_f32 v[114:115], v[160:161], v[122:123], v[114:115]
	v_pk_fma_f32 v[120:121], v[140:141], v[104:105], v[120:121]
	v_mul_f32_e32 v164, 0xbfb8aa3b, v114
	v_mul_f32_e32 v165, 0xbfb8aa3b, v115
	v_exp_f32_e32 v164, v164
	v_exp_f32_e32 v165, v165
	s_mov_b32 s3, 0xd000
	v_pk_fma_f32 v[116:117], v[130:131], v[116:117], v[142:143]
	v_add_f32_e32 v164, 1.0, v164
	v_add_f32_e32 v165, 1.0, v165
	v_rcp_f32_e32 v164, v164
	v_rcp_f32_e32 v165, v165
	v_pk_fma_f32 v[116:117], v[134:135], v[102:103], v[116:117]
	v_pk_fma_f32 v[112:113], v[132:133], v[112:113], v[144:145]
	v_pk_fma_f32 v[116:117], v[138:139], v[198:199], v[116:117]
	v_pk_mul_f32 v[114:115], v[114:115], v[164:165]
	v_pk_fma_f32 v[112:113], v[136:137], v[104:105], v[112:113]
	v_pk_mul_f32 v[114:115], v[152:153], v[114:115]
	v_pk_mul_f32 v[152:153], v[98:99], v[106:107] op_sel:[0,1]
	v_pk_fma_f32 v[98:99], v[146:147], v[178:179], v[166:167]
	v_cvt_pk_bf16_f32 v115, v114, v115
	v_cvt_pk_bf16_f32 v114, v110, v111
	v_add_co_u32_e32 v110, vcc, s49, v222
	v_pk_fma_f32 v[98:99], v[154:155], v[170:171], v[98:99]
	s_nop 0
	v_addc_co_u32_e32 v111, vcc, 0, v223, vcc
	v_pk_fma_f32 v[98:99], v[158:159], v[152:153], v[98:99]
	global_store_dwordx2 v[110:111], v[114:115], off
	v_pk_mul_f32 v[114:115], v[100:101], v[106:107] op_sel:[0,1]
	v_mul_f32_e32 v100, 0xbfb8aa3b, v98
	v_mul_f32_e32 v101, 0xbfb8aa3b, v99
	v_exp_f32_e32 v100, v100
	v_exp_f32_e32 v101, v101
	v_pk_fma_f32 v[112:113], v[140:141], v[200:201], v[112:113]
	v_pk_fma_f32 v[102:103], v[130:131], v[102:103], v[142:143]
	v_add_f32_e32 v100, 1.0, v100
	v_add_f32_e32 v101, 1.0, v101
	v_rcp_f32_e32 v100, v100
	v_rcp_f32_e32 v101, v101
	v_pk_fma_f32 v[102:103], v[134:135], v[198:199], v[102:103]
	v_pk_fma_f32 v[104:105], v[132:133], v[104:105], v[144:145]
	v_pk_fma_f32 v[102:103], v[138:139], v[194:195], v[102:103]
	v_pk_mul_f32 v[98:99], v[98:99], v[100:101]
	v_pk_fma_f32 v[100:101], v[148:149], v[162:163], v[168:169]
	v_pk_mul_f32 v[98:99], v[124:125], v[98:99]
	v_pk_fma_f32 v[100:101], v[156:157], v[122:123], v[100:101]
	v_pk_fma_f32 v[104:105], v[136:137], v[200:201], v[104:105]
	v_pk_fma_f32 v[100:101], v[160:161], v[114:115], v[100:101]
	v_pk_fma_f32 v[104:105], v[140:141], v[196:197], v[104:105]
	v_mul_f32_e32 v124, 0xbfb8aa3b, v100
	v_mul_f32_e32 v125, 0xbfb8aa3b, v101
	v_exp_f32_e32 v124, v124
	v_exp_f32_e32 v125, v125
	v_mov_b32_e32 v228, v108
	v_mov_b32_e32 v229, v108
	v_add_f32_e32 v124, 1.0, v124
	v_add_f32_e32 v125, 1.0, v125
	v_rcp_f32_e32 v124, v124
	v_rcp_f32_e32 v125, v125
	v_mov_b32_e32 v226, v109
	v_mov_b32_e32 v227, v109
	v_pk_mul_f32 v[92:93], v[92:93], v[228:229]
	v_pk_mul_f32 v[100:101], v[100:101], v[124:125]
	v_pk_mul_f32 v[88:89], v[88:89], v[226:227]
	v_pk_mul_f32 v[100:101], v[120:121], v[100:101]
	v_pk_mul_f32 v[80:81], v[80:81], v[228:229]
	v_cvt_pk_bf16_f32 v101, v100, v101
	v_cvt_pk_bf16_f32 v100, v98, v99
	v_add_co_u32_e32 v98, vcc, s3, v222
	s_mov_b32 s3, 0x10000
	s_nop 0
	v_addc_co_u32_e32 v99, vcc, 0, v223, vcc
	global_store_dwordx2 v[98:99], v[100:101], off offset:3072
	v_pk_fma_f32 v[100:101], v[146:147], v[170:171], v[166:167]
	v_pk_mul_f32 v[72:73], v[72:73], v[226:227]
	v_pk_fma_f32 v[100:101], v[154:155], v[152:153], v[100:101]
	s_nop 0
	v_pk_fma_f32 v[100:101], v[158:159], v[186:187], v[100:101]
	s_nop 0
	v_mul_f32_e32 v120, 0xbfb8aa3b, v100
	v_mul_f32_e32 v121, 0xbfb8aa3b, v101
	v_exp_f32_e32 v120, v120
	v_exp_f32_e32 v121, v121
	v_add_f32_e32 v120, 1.0, v120
	v_add_f32_e32 v121, 1.0, v121
	v_rcp_f32_e32 v120, v120
	v_rcp_f32_e32 v121, v121
	s_nop 0
	v_pk_mul_f32 v[100:101], v[100:101], v[120:121]
	s_nop 0
	v_pk_mul_f32 v[100:101], v[116:117], v[100:101]
	v_pk_fma_f32 v[116:117], v[148:149], v[122:123], v[168:169]
	ds_bpermute_b32 v122, v250, v80
	v_pk_fma_f32 v[116:117], v[156:157], v[114:115], v[116:117]
	ds_bpermute_b32 v123, v250, v81
	v_pk_fma_f32 v[116:117], v[160:161], v[188:189], v[116:117]
	s_nop 0
	v_mul_f32_e32 v120, 0xbfb8aa3b, v116
	v_mul_f32_e32 v121, 0xbfb8aa3b, v117
	v_exp_f32_e32 v120, v120
	v_exp_f32_e32 v121, v121
	v_add_f32_e32 v120, 1.0, v120
	v_add_f32_e32 v121, 1.0, v121
	v_rcp_f32_e32 v120, v120
	v_rcp_f32_e32 v121, v121
	s_nop 0
	v_pk_mul_f32 v[116:117], v[116:117], v[120:121]
	s_nop 0
	v_pk_mul_f32 v[112:113], v[112:113], v[116:117]
	ds_bpermute_b32 v120, v250, v92
	v_cvt_pk_bf16_f32 v113, v112, v113
	v_cvt_pk_bf16_f32 v112, v100, v101
	v_add_co_u32_e32 v100, vcc, s3, v222
	s_mov_b32 s3, 0x13000
	s_nop 0
	v_addc_co_u32_e32 v101, vcc, 0, v223, vcc
	global_store_dwordx2 v[100:101], v[112:113], off offset:2048
	v_pk_fma_f32 v[112:113], v[146:147], v[152:153], v[166:167]
	ds_bpermute_b32 v121, v250, v93
	v_pk_fma_f32 v[112:113], v[154:155], v[186:187], v[112:113]
	s_nop 0
	v_pk_fma_f32 v[112:113], v[158:159], v[182:183], v[112:113]
	s_nop 0
	v_mul_f32_e32 v116, 0xbfb8aa3b, v112
	v_mul_f32_e32 v117, 0xbfb8aa3b, v113
	v_exp_f32_e32 v116, v116
	v_exp_f32_e32 v117, v117
	v_add_f32_e32 v116, 1.0, v116
	v_add_f32_e32 v117, 1.0, v117
	v_rcp_f32_e32 v116, v116
	v_rcp_f32_e32 v117, v117
	s_nop 0
	v_pk_mul_f32 v[112:113], v[112:113], v[116:117]
	s_nop 0
	v_pk_mul_f32 v[102:103], v[102:103], v[112:113]
	v_pk_fma_f32 v[112:113], v[148:149], v[114:115], v[168:169]
	s_nop 0
	v_pk_fma_f32 v[112:113], v[156:157], v[188:189], v[112:113]
	s_nop 0
	v_pk_fma_f32 v[112:113], v[160:161], v[184:185], v[112:113]
	s_nop 0
	v_mul_f32_e32 v114, 0xbfb8aa3b, v112
	v_mul_f32_e32 v115, 0xbfb8aa3b, v113
	v_exp_f32_e32 v114, v114
	v_exp_f32_e32 v115, v115
	v_add_f32_e32 v114, 1.0, v114
	v_add_f32_e32 v115, 1.0, v115
	v_rcp_f32_e32 v114, v114
	v_rcp_f32_e32 v115, v115
	s_nop 0
	v_pk_mul_f32 v[112:113], v[112:113], v[114:115]
	s_nop 0
	v_pk_mul_f32 v[104:105], v[104:105], v[112:113]
	ds_bpermute_b32 v112, v250, v72
	v_cvt_pk_bf16_f32 v105, v104, v105
	v_cvt_pk_bf16_f32 v104, v102, v103
	v_add_co_u32_e32 v102, vcc, s3, v222
	ds_bpermute_b32 v113, v250, v73
	s_nop 0
	v_addc_co_u32_e32 v103, vcc, 0, v223, vcc
	global_store_dwordx2 v[102:103], v[104:105], off offset:1024
	v_mov_b32_e32 v102, v108
	v_mov_b32_e32 v103, v108
	v_mov_b32_e32 v108, v109
	v_pk_mul_f32 v[94:95], v[94:95], v[102:103]
	v_pk_mul_f32 v[90:91], v[90:91], v[108:109]
	v_pk_mul_f32 v[82:83], v[82:83], v[102:103]
	v_pk_mul_f32 v[74:75], v[74:75], v[108:109]
	ds_bpermute_b32 v108, v250, v88
	ds_bpermute_b32 v109, v250, v89
	ds_bpermute_b32 v114, v250, v94
	ds_bpermute_b32 v102, v250, v90
	ds_bpermute_b32 v116, v250, v82
	ds_bpermute_b32 v104, v250, v74
	ds_bpermute_b32 v115, v250, v95
	ds_bpermute_b32 v103, v250, v91
	ds_bpermute_b32 v117, v250, v83
	ds_bpermute_b32 v105, v250, v75
	s_and_saveexec_b64 s[14:15], s[8:9]
	s_cbranch_execz .LBB0_1108
;     __device__ __forceinline__ void operator()(const f32x4 (&acc)[2][2][4][2], const Unit& u, int wr, int wc, int fr, int fq) const {
;     ...
;             if (fr == 15) { *(f32x4*)(hrow + 2 * DFF2 + 4 * n) = v6; *(f32x4*)(hrow + 2 * DFF2 + HALF + 4 * n) = g6; *(f32x4*)(hrow + 3 * DFF2 + 4 * n) = v7; *(f32x4*)(hrow + 3 * DFF2 + HALF + 4 * n) = g7; }
	v_add_co_u32_e32 v124, vcc, 0x16000, v224
	s_nop 1
	v_addc_co_u32_e32 v125, vcc, 0, v225, vcc
	global_store_dwordx4 v[124:125], v[92:95], off offset:16
	global_store_dwordx4 v[124:125], v[80:83], off offset:528
	v_add_co_u32_e32 v124, vcc, 0x21000, v224
	s_nop 1
	v_addc_co_u32_e32 v125, vcc, 0, v225, vcc
	global_store_dwordx4 v[124:125], v[88:91], off offset:16
	global_store_dwordx4 v[124:125], v[72:75], off offset:528
